# attention: query blocks reassigned so each SIMD's wave pair (w, w+4) gets blocks j and 255-j (equal causal work per workgroup)
# speedup vs baseline: 1.0052x; 1.0052x over previous
.LBB0_293:
	v_mov_b32_e32 v92, v206
	v_mov_b32_e32 v125, v177
	v_ashrrev_i32_e32 v0, 6, v92
	v_lshl_add_u32 v6, s20, 3, v0
	v_bfe_u32 v4, v6, 3, 5
	v_and_b32_e32 v5, 3, v6
	v_lshl_or_b32 v4, v4, 2, v5
	v_sub_u32_e32 v5, 0xff, v4
	v_and_b32_e32 v7, 4, v6
	v_cmp_ne_u32_e32 vcc, 0, v7
	v_and_b32_e32 v6, 0xffffff00, v6
	v_cndmask_b32_e32 v4, v4, v5, vcc
	v_or_b32_e32 v6, v6, v4
	v_mov_b32_e32 v0, v206
	v_and_b32_e32 v138, 0xff, v6
	v_and_b32_e32 v137, 31, v0
	v_bfe_u32 v4, v0, 5, 1
	v_lshlrev_b32_e32 v5, 5, v138
	v_lshlrev_b32_e32 v0, 3, v6
	v_and_b32_e32 v7, 0xffffe000, v0
	v_or_b32_e32 v8, v5, v137
	v_ashrrev_i32_e32 v6, 2, v6
	v_or_b32_e32 v136, v8, v7
	v_mov_b64_e32 v[0:1], s[76:77]
	v_and_b32_e32 v9, 0xc0, v6
	v_mad_i64_i32 v[2:3], s[2:3], v136, s13, v[0:1]
	v_lshlrev_b32_e32 v124, 1, v9
	v_lshl_add_u64 v[126:127], v[2:3], 0, v[124:125]
	v_lshlrev_b32_e32 v176, 4, v4
	v_lshl_add_u64 v[2:3], v[126:127], 0, v[176:177]
	v_mad_i64_i32 v[0:1], s[2:3], v7, s13, v[0:1]
	global_load_dwordx4 v[48:51], v[2:3], off
	global_load_dwordx4 v[52:55], v[2:3], off offset:32
	global_load_dwordx4 v[56:59], v[2:3], off offset:64
	global_load_dwordx4 v[60:63], v[2:3], off offset:96
	v_and_b32_e32 v2, 0xffffffc0, v6
	v_lshl_add_u64 v[0:1], v[0:1], 0, v[124:125]
	v_lshl_add_u64 v[128:129], v[0:1], 0, v[176:177]
	v_ashrrev_i32_e32 v3, 31, v2
	v_mul_u32_u24_e32 v0, 0xa00, v8
	v_lshlrev_b64 v[6:7], 14, v[2:3]
	v_lshlrev_b32_e32 v176, 1, v0
	v_lshl_add_u64 v[8:9], v[128:129], 0, v[176:177]
	v_lshl_add_u64 v[6:7], s[98:99], 0, v[6:7]
	v_lshlrev_b32_e32 v176, 6, v138
	global_load_dwordx4 v[0:3], v[8:9], off offset:512
	global_load_dwordx4 v[28:31], v[8:9], off offset:544
	global_load_dwordx4 v[20:23], v[8:9], off offset:576
	global_load_dwordx4 v[24:27], v[8:9], off offset:608
	v_lshl_add_u64 v[8:9], v[6:7], 0, v[176:177]
	v_lshlrev_b32_e32 v176, 5, v4
	v_lshl_add_u64 v[8:9], v[8:9], 0, v[176:177]
	v_lshlrev_b32_e32 v10, 14, v137
	v_mov_b32_e32 v11, v177
	v_lshlrev_b32_e32 v12, 13, v137
	v_lshl_add_u64 v[10:11], v[8:9], 0, v[10:11]
	global_load_dwordx4 v[36:39], v[10:11], off offset:16
	global_load_dwordx4 v[16:19], v[10:11], off
	v_or_b32_e32 v10, 0x40000, v12
	v_lshlrev_b32_e32 v130, 1, v10
	v_mov_b32_e32 v131, v177
	v_lshl_add_u64 v[8:9], v[8:9], 0, v[130:131]
	global_load_dwordx4 v[40:43], v[8:9], off offset:16
	global_load_dwordx4 v[44:47], v[8:9], off
	v_lshl_add_u64 v[132:133], v[6:7], 0, v[176:177]
	v_cmp_ne_u32_e64 s[36:37], 0, v138
	v_lshlrev_b32_e32 v134, 1, v12
	s_and_saveexec_b64 s[2:3], s[36:37]
	s_xor_b64 s[2:3], exec, s[2:3]
	s_cbranch_execz .LBB0_295
	v_subrev_u32_e32 v176, 32, v5
	v_or_b32_e32 v5, v176, v137
	v_mad_u64_u32 v[6:7], s[4:5], v5, s13, v[128:129]
	global_load_dwordx4 v[32:35], v[6:7], off offset:512
	global_load_dwordx4 v[88:91], v[6:7], off offset:544
	global_load_dwordx4 v[84:87], v[6:7], off offset:576
	global_load_dwordx4 v[80:83], v[6:7], off offset:608
	v_lshl_add_u64 v[6:7], v[176:177], 1, v[132:133]
	v_mov_b32_e32 v135, v177
	v_lshl_add_u64 v[8:9], v[6:7], 0, v[134:135]
	v_lshl_add_u64 v[6:7], v[6:7], 0, v[130:131]
	global_load_dwordx4 v[64:67], v[8:9], off offset:16
	global_load_dwordx4 v[76:79], v[8:9], off
	global_load_dwordx4 v[68:71], v[6:7], off offset:16
	global_load_dwordx4 v[72:75], v[6:7], off

.LBB0_297:
	s_or_b64 exec, exec, s[2:3]
	v_and_b32_e32 v6, 64, v210
	v_xor_b32_e32 v5, 32, v210
	v_add_u32_e32 v6, 64, v6
	v_cmp_lt_i32_e32 vcc, v5, v6
	v_lshlrev_b32_e32 v125, 2, v4
	v_cmp_lt_u32_e64 s[38:39], v125, v137
	v_cndmask_b32_e32 v5, v210, v5, vcc
	v_lshlrev_b32_e32 v139, 2, v5
	v_cmp_eq_u32_e32 vcc, 0, v4
	s_waitcnt vmcnt(0)
	v_mfma_f32_32x32x16_bf16 v[0:15], v[0:3], v[48:51], 0
	v_mfma_f32_32x32x16_bf16 v[0:15], v[28:31], v[52:55], v[0:15]
	v_mfma_f32_32x32x16_bf16 v[0:15], v[20:23], v[56:59], v[0:15]
	v_mfma_f32_32x32x16_bf16 v[0:15], v[24:27], v[60:63], v[0:15]
	s_nop 11
	v_mul_f32_e32 v0, 0x3e38aa3b, v0
	v_min_f32_e32 v0, 0x42700000, v0
	v_exp_f32_e32 v20, v0
	s_nop 0
	v_add_f32_e32 v20, 1.0, v20
	v_log_f32_e32 v21, v20
	s_nop 0
	v_sub_f32_e32 v0, v0, v21
	v_cndmask_b32_e64 v20, v217, v0, s[38:39]
	v_mul_f32_e32 v0, 0x3e38aa3b, v1
	v_min_f32_e32 v0, 0x42700000, v0
	v_exp_f32_e32 v1, v0
	v_cndmask_b32_e64 v23, 0, v21, s[38:39]
	v_or_b32_e32 v21, 1, v125
	v_cmp_lt_u32_e64 s[38:39], v21, v137
	v_add_f32_e32 v1, 1.0, v1
	v_log_f32_e32 v1, v1
	s_nop 0
	v_sub_f32_e32 v0, v0, v1
	v_cndmask_b32_e64 v22, v217, v0, s[38:39]
	v_mul_f32_e32 v0, 0x3e38aa3b, v2
	v_min_f32_e32 v0, 0x42700000, v0
	v_cndmask_b32_e64 v21, 0, v1, s[38:39]
	v_exp_f32_e32 v1, v0
	v_or_b32_e32 v2, 2, v125
	v_cmp_lt_u32_e64 s[38:39], v2, v137
	v_or_b32_e32 v2, 3, v125
	v_add_f32_e32 v1, 1.0, v1
	v_log_f32_e32 v1, v1
	s_nop 0
	v_sub_f32_e32 v0, v0, v1
	v_cndmask_b32_e64 v25, v217, v0, s[38:39]
	v_mul_f32_e32 v0, 0x3e38aa3b, v3
	v_min_f32_e32 v0, 0x42700000, v0
	v_cndmask_b32_e64 v24, 0, v1, s[38:39]
	v_exp_f32_e32 v1, v0
	v_cmp_lt_u32_e64 s[38:39], v2, v137
	v_or_b32_e32 v2, 8, v125
	v_or_b32_e32 v3, 9, v125
	v_add_f32_e32 v1, 1.0, v1
	v_log_f32_e32 v1, v1
	s_nop 0
	v_sub_f32_e32 v0, v0, v1
	v_cndmask_b32_e64 v27, v217, v0, s[38:39]
	v_mul_f32_e32 v0, 0x3e38aa3b, v4
	v_min_f32_e32 v0, 0x42700000, v0
	v_cndmask_b32_e64 v26, 0, v1, s[38:39]
	v_exp_f32_e32 v1, v0
	v_cmp_lt_u32_e64 s[38:39], v2, v137
	v_or_b32_e32 v4, 10, v125
	v_add_f32_e32 v1, 1.0, v1
	v_log_f32_e32 v1, v1
	s_nop 0
	v_sub_f32_e32 v0, v0, v1
	v_cndmask_b32_e64 v28, v217, v0, s[38:39]
	v_mul_f32_e32 v0, 0x3e38aa3b, v5
	v_min_f32_e32 v0, 0x42700000, v0
	v_cndmask_b32_e64 v2, 0, v1, s[38:39]
	v_exp_f32_e32 v1, v0
	v_cmp_lt_u32_e64 s[38:39], v3, v137
	v_or_b32_e32 v5, 18, v125
	v_add_f32_e32 v1, 1.0, v1
	v_log_f32_e32 v1, v1
	s_nop 0
	v_sub_f32_e32 v0, v0, v1
	v_cndmask_b32_e64 v29, v217, v0, s[38:39]
	v_cndmask_b32_e64 v0, 0, v1, s[38:39]
	v_mul_f32_e32 v1, 0x3e38aa3b, v6
	v_min_f32_e32 v1, 0x42700000, v1
	v_exp_f32_e32 v3, v1
	v_cmp_lt_u32_e64 s[38:39], v4, v137
	v_or_b32_e32 v4, 11, v125
	v_add_f32_e32 v3, 1.0, v3
	v_log_f32_e32 v3, v3
	s_nop 0
	v_sub_f32_e32 v1, v1, v3
	v_cndmask_b32_e64 v31, v217, v1, s[38:39]
	v_mul_f32_e32 v1, 0x3e38aa3b, v7
	v_min_f32_e32 v1, 0x42700000, v1
	v_cndmask_b32_e64 v30, 0, v3, s[38:39]
	v_exp_f32_e32 v3, v1
	v_cmp_lt_u32_e64 s[38:39], v4, v137
	v_or_b32_e32 v4, 16, v125
	v_or_b32_e32 v7, 25, v125
	v_add_f32_e32 v3, 1.0, v3
	v_log_f32_e32 v3, v3
	s_nop 0
	v_sub_f32_e32 v1, v1, v3
	v_cndmask_b32_e64 v96, v217, v1, s[38:39]
	v_mul_f32_e32 v1, 0x3e38aa3b, v8
	v_min_f32_e32 v1, 0x42700000, v1
	v_cndmask_b32_e64 v97, 0, v3, s[38:39]
	v_exp_f32_e32 v3, v1
	v_cmp_lt_u32_e64 s[38:39], v4, v137
	v_or_b32_e32 v4, 17, v125
	v_add_f32_e32 v8, v30, v97
	v_add_f32_e32 v3, 1.0, v3
	v_log_f32_e32 v3, v3
	s_nop 0
	v_sub_f32_e32 v1, v1, v3
	v_cndmask_b32_e64 v98, v217, v1, s[38:39]
	v_mul_f32_e32 v1, 0x3e38aa3b, v9
	v_min_f32_e32 v1, 0x42700000, v1
	v_cndmask_b32_e64 v6, 0, v3, s[38:39]
	v_exp_f32_e32 v3, v1
	v_cmp_lt_u32_e64 s[38:39], v4, v137
	v_add_f32_e32 v3, 1.0, v3
	v_log_f32_e32 v3, v3
	s_nop 0
	v_sub_f32_e32 v1, v1, v3
	v_cndmask_b32_e64 v99, v217, v1, s[38:39]
	v_mul_f32_e32 v1, 0x3e38aa3b, v10
	v_min_f32_e32 v1, 0x42700000, v1
	v_cndmask_b32_e64 v4, 0, v3, s[38:39]
	v_exp_f32_e32 v3, v1
	v_cmp_lt_u32_e64 s[38:39], v5, v137
	v_or_b32_e32 v5, 19, v125
	v_add_f32_e32 v3, 1.0, v3
	v_log_f32_e32 v3, v3
	s_nop 0
	v_sub_f32_e32 v1, v1, v3
	v_cndmask_b32_e64 v100, v217, v1, s[38:39]
	v_mul_f32_e32 v1, 0x3e38aa3b, v11
	v_min_f32_e32 v1, 0x42700000, v1
	v_cndmask_b32_e64 v101, 0, v3, s[38:39]
	v_exp_f32_e32 v3, v1
	v_cmp_lt_u32_e64 s[38:39], v5, v137
	v_or_b32_e32 v5, 24, v125
	v_add_f32_e32 v3, 1.0, v3
	v_log_f32_e32 v3, v3
	s_nop 0
	v_sub_f32_e32 v1, v1, v3
	v_cndmask_b32_e64 v102, v217, v1, s[38:39]
	v_mul_f32_e32 v1, 0x3e38aa3b, v12
	v_min_f32_e32 v1, 0x42700000, v1
	v_cndmask_b32_e64 v103, 0, v3, s[38:39]
	v_exp_f32_e32 v3, v1
	v_cmp_lt_u32_e64 s[38:39], v5, v137
	v_add_f32_e32 v10, v101, v103
	v_add_f32_e32 v3, 1.0, v3
	v_log_f32_e32 v3, v3
	s_nop 0
	v_sub_f32_e32 v1, v1, v3
	v_cndmask_b32_e64 v12, v217, v1, s[38:39]
	v_cndmask_b32_e64 v1, 0, v3, s[38:39]
	v_mul_f32_e32 v3, 0x3e38aa3b, v13
	v_min_f32_e32 v3, 0x42700000, v3
	v_exp_f32_e32 v5, v3
	v_cmp_lt_u32_e64 s[38:39], v7, v137
	v_or_b32_e32 v7, 26, v125
	v_add_f32_e32 v5, 1.0, v5
	v_log_f32_e32 v5, v5
	s_nop 0
	v_sub_f32_e32 v3, v3, v5
	v_cndmask_b32_e64 v13, v217, v3, s[38:39]
	v_mul_f32_e32 v3, 0x3e38aa3b, v14
	v_min_f32_e32 v3, 0x42700000, v3
	v_cndmask_b32_e64 v104, 0, v5, s[38:39]
	v_exp_f32_e32 v5, v3
	v_cmp_lt_u32_e64 s[38:39], v7, v137
	v_or_b32_e32 v7, 27, v125
	v_add_f32_e32 v5, 1.0, v5
	v_log_f32_e32 v5, v5
	s_nop 0
	v_sub_f32_e32 v3, v3, v5
	v_cndmask_b32_e64 v14, v217, v3, s[38:39]
	v_mul_f32_e32 v3, 0x3e38aa3b, v15
	v_min_f32_e32 v3, 0x42700000, v3
	v_cndmask_b32_e64 v105, 0, v5, s[38:39]
	v_exp_f32_e32 v5, v3
	v_cmp_lt_u32_e64 s[38:39], v7, v137
	v_add_f32_e32 v7, v1, v104
	v_add_f32_e32 v5, 1.0, v5
	v_log_f32_e32 v5, v5
	s_nop 0
	v_sub_f32_e32 v3, v3, v5
	v_cndmask_b32_e64 v15, v217, v3, s[38:39]
	v_cndmask_b32_e64 v106, 0, v5, s[38:39]
	v_add_f32_e32 v3, v23, v21
	v_add_f32_e32 v5, v24, v26
	v_add_f32_e32 v93, v3, v5
	v_add_f32_e32 v5, v105, v106
	v_pk_add_f32 v[6:7], v[6:7], v[4:5]
	ds_bpermute_b32 v11, v139, v7
	ds_bpermute_b32 v94, v139, v93
	s_waitcnt lgkmcnt(1)
	v_pk_add_f32 v[6:7], v[6:7], v[10:11]
	ds_bpermute_b32 v9, v139, v6
	v_mov_b32_e32 v3, v6
	v_mov_b32_e32 v1, v7
	v_pk_add_f32 v[2:3], v[2:3], v[0:1]
	s_waitcnt lgkmcnt(0)
	v_pk_add_f32 v[2:3], v[2:3], v[8:9]
	ds_bpermute_b32 v1, v139, v2
	v_add_f32_e32 v2, v2, v3
	s_waitcnt lgkmcnt(0)
	v_add_f32_e32 v95, v2, v1
	v_cndmask_b32_e32 v1, 0, v1, vcc
	v_add_f32_e32 v1, v1, v3
	v_cndmask_b32_e32 v2, 0, v94, vcc
	v_add_f32_e32 v1, 0, v1
	v_add_f32_e32 v2, v2, v95
	v_sub_f32_e32 v3, v96, v1
	v_add_f32_e32 v1, v97, v1
	v_add_f32_e32 v2, 0, v2
	v_sub_f32_e32 v10, v31, v1
	v_add_f32_e32 v1, v30, v1
	v_sub_f32_e32 v5, v27, v2
	v_add_f32_e32 v2, v26, v2
	v_add_f32_e32 v0, v0, v1
	v_sub_f32_e32 v6, v25, v2
	v_add_f32_e32 v2, v24, v2
	v_sub_f32_e32 v0, v28, v0
	v_sub_f32_e32 v8, v22, v2
	v_add_f32_e32 v2, v21, v2
	v_exp_f32_e32 v21, v0
	v_cndmask_b32_e32 v0, 0, v9, vcc
	v_add_f32_e32 v0, v0, v7
	v_add_f32_e32 v0, 0, v0
	v_sub_f32_e32 v2, v20, v2
	v_sub_f32_e32 v20, v29, v1
	v_sub_f32_e32 v1, v102, v0
	v_add_f32_e32 v0, v103, v0
	v_exp_f32_e32 v96, v1
	v_sub_f32_e32 v1, v100, v0
	v_add_f32_e32 v0, v101, v0
	v_exp_f32_e32 v97, v1
	v_sub_f32_e32 v1, v99, v0
	v_add_f32_e32 v0, v4, v0
	v_sub_f32_e32 v0, v98, v0
	v_exp_f32_e32 v98, v0
	v_add_f32_e32 v0, 0, v11
	v_cndmask_b32_e32 v0, 0, v0, vcc
	v_exp_f32_e32 v5, v5
	v_exp_f32_e32 v6, v6
	v_exp_f32_e32 v8, v8
	v_exp_f32_e32 v2, v2
	v_exp_f32_e32 v3, v3
	v_exp_f32_e32 v10, v10
	v_exp_f32_e32 v20, v20
	v_exp_f32_e32 v99, v1
	v_sub_f32_e32 v1, v15, v0
	v_add_f32_e32 v0, v0, v106
	v_exp_f32_e32 v100, v1
	v_sub_f32_e32 v1, v14, v0
	v_add_f32_e32 v0, v105, v0
	v_exp_f32_e32 v101, v1
	v_sub_f32_e32 v1, v13, v0
	v_add_f32_e32 v0, v104, v0
	v_sub_f32_e32 v0, v12, v0
	v_exp_f32_e32 v102, v1
	v_exp_f32_e32 v103, v0
	v_cvt_pk_bf16_f32 v0, v2, v8
	v_cvt_pk_bf16_f32 v1, v6, v5
	v_cvt_pk_bf16_f32 v2, v21, v20
	v_cvt_pk_bf16_f32 v3, v10, v3
	s_nop 1
	v_mfma_f32_32x32x16_bf16 v[16:31], v[16:19], v[0:3], 0
	v_mfma_f32_32x32x16_bf16 v[0:15], v[44:47], v[0:3], 0
	v_cvt_pk_bf16_f32 v44, v98, v99
	v_cvt_pk_bf16_f32 v45, v97, v96
	v_cvt_pk_bf16_f32 v46, v103, v102
	v_cvt_pk_bf16_f32 v47, v101, v100
	s_nop 1
	v_mfma_f32_32x32x16_bf16 v[16:31], v[36:39], v[44:47], v[16:31]
	v_mfma_f32_32x32x16_bf16 v[0:15], v[40:43], v[44:47], v[0:15]
	s_and_saveexec_b64 s[4:5], s[36:37]
	s_cbranch_execz .LBB0_188
	v_add_f32_e32 v36, v93, v95
	v_add_f32_e32 v36, v36, v94
	s_mov_b32 s2, 0x43170000
	v_cmp_lt_f32_e64 s[36:37], s2, v36
	s_cmp_eq_u64 s[36:37], exec
	s_cbranch_scc1 .LBB0_188
	v_add_f32_e32 v140, 0, v36
	v_mov_b32_e32 v36, v138
	v_and_b32_e32 v36, 0xff, v36
	v_not_b32_e32 v37, 63
	v_mov_b64_e32 v[94:95], v[82:83]
	v_mov_b64_e32 v[98:99], v[86:87]
	v_mov_b64_e32 v[102:103], v[90:91]
	v_mov_b64_e32 v[106:107], v[34:35]
	v_lshl_add_u32 v176, v36, 5, v37
	s_mov_b64 s[38:39], 0
	v_mov_b64_e32 v[92:93], v[80:81]
	v_mov_b64_e32 v[96:97], v[84:85]
	v_mov_b64_e32 v[100:101], v[88:89]
	v_mov_b64_e32 v[104:105], v[32:33]
	s_branch .LBB0_301
